# static priority raise moved to the first-dispatched half (waves 0-3) in the attention A loop instead of waves 4-7
# speedup vs baseline: 1.0099x; 1.0099x over previous
; __device__ __forceinline__ int v_rd_base(int lane) { return ((lane & 3) << 3) | (((lane >> 2) & 3) << 6) | (((lane >> 4) & 1) << 5) | (((lane >> 5) & 1) << 8); }
; __device__ __forceinline__ void unit(const bf16* Qb, const bf16* __restrict__ Kh, const bf16* __restrict__ Vh, bf16* Ob, float lam, float post, const float* __restrict__ gsub, char* lds) {
;   int tid_ = threadIdx.x; asm volatile("" : "+v"(tid_));
;   const int tid = tid_, wid = __builtin_amdgcn_readfirstlane(tid >> 6), lane = tid & 63, r32 = lane & 31, hi = lane >> 5;
;   const int mp = wid >> 2, wq = wid & 3;
;   typedef __attribute__((address_space(3))) unsigned lds_u32;
;   float* ws = (float*)(lds + WS_OFF) + wid * 64; float* li_l = ws; float* al_l = ws + 32;
;   float m_reg = 0.f, l_reg = 0; f32x16 o[4] = {}; bf16x8 qr[4]; f32x16 negm = f32x16{};
;   const bf16* Qw = Qb + (long)(wq * QBLK + r32) * LD + mp * 64 + hi * 8;
; #pragma unroll
;   for (int d0 = 0; d0 < 4; ++d0) qr[d0] = ld8(Qw + d0 * 16);
;   const int vb0 = (int)(uintptr_t)lds + v_rd_base(lane);
;   unsigned kof[2], vof[2];
; #pragma unroll
;   for (int n = 0; n < 2; ++n) { const int c = 2 * wid + n;
;     { const int row = 4 * c + (lane >> 4), lc = (lane & 15) ^ (row & 15); kof[n] = (unsigned)(row * LD + 8 * lc) * 2u; }
;     { const int st = 2 * c + (lane >> 5), p = lane & 31, k = 8 * (st >> 2) + (p >> 2), col = 32 * (st & 3) + 8 * (p & 3); vof[n] = (unsigned)(k * LD + col) * 2u; } }
;     ...
;   f32x16 pA0, pA1, pB0, pB1; float alA, alB; bf16x8 pa0, pa1, pa2, pa3; constexpr int NT = 4096 / KVBLK;
;   DMA_TILE(0, 0); DMA_TILE(1, 32768); DMA_TILE(2, 65536);
;   asm volatile("s_waitcnt vmcnt(0)" ::: "memory"); __syncthreads();
.LBB0_196:
	s_lshl_b32 s8, s24, 1
	s_and_b32 s10, s8, 0x300
	s_ashr_i32 s8, s0, 7
	s_ashr_i32 s9, s8, 31
	s_lshl_b32 s11, s0, 17
	s_and_b32 s11, s11, 0x3e0000
	s_lshl_b64 vcc, s[8:9], 22
	s_add_u32 s8, s42, vcc_lo
	s_addc_u32 s9, s43, vcc_hi
	s_add_u32 s8, s8, s11
	s_addc_u32 s9, s9, 0
	s_lshl_b32 s11, s0, 3
	s_and_b32 s11, s11, 0x300
	s_add_u32 s22, s8, s11
	s_addc_u32 s23, s9, 0
	s_add_u32 s8, s29, vcc_lo
	s_addc_u32 s9, s20, vcc_hi
	s_add_u32 s40, s8, s11
	s_addc_u32 s41, s9, 0
	s_add_u32 s8, s3, vcc_lo
	s_addc_u32 s9, s1, vcc_hi
	s_add_u32 s48, s8, s11
	v_mov_b32_e32 v165, v218
	s_addc_u32 s49, s9, 0
	v_mov_b32_e32 v167, v189
	v_readfirstlane_b32 s9, v165
	s_ashr_i32 s8, s9, 6
	s_lshl_b32 s11, s8, 5
	v_and_b32_e32 v178, 31, v165
	s_and_b32 s11, s11, 0x60
	s_ashr_i32 s12, s9, 8
	v_or_b32_e32 v0, s11, v178
	v_lshlrev_b32_e32 v188, 10, v0
	s_lshl_b32 s30, s12, 6
	v_bfe_u32 v179, v165, 5, 1
	v_lshl_add_u64 v[0:1], s[22:23], 0, v[188:189]
	s_ashr_i32 s31, s30, 31
	v_lshl_add_u64 v[0:1], s[30:31], 1, v[0:1]
	v_lshlrev_b32_e32 v166, 4, v179
	v_lshl_add_u64 v[0:1], v[0:1], 0, v[166:167]
	global_load_dwordx4 v[158:161], v[0:1], off
	global_load_dwordx4 v[154:157], v[0:1], off offset:32
	global_load_dwordx4 v[150:153], v[0:1], off offset:64
	global_load_dwordx4 v[146:149], v[0:1], off offset:96
	s_lshl_b32 s13, s8, 3
	v_bfe_u32 v52, v165, 4, 2
	v_lshlrev_b32_e32 v182, 8, v178
	v_bitop3_b32 v1, s13, v165, v52 bitop3:0x36
	s_lshl_b32 s11, s8, 13
	v_and_b32_e32 v0, 0x1c00, v182
	v_lshlrev_b32_e32 v1, 4, v1
	v_or_b32_e32 v54, s11, v0
	v_or_b32_e32 v0, s13, v52
	v_and_b32_e32 v55, 0xf0, v1
	s_lshl_b32 s13, s8, 11
	v_lshlrev_b32_e32 v8, 4, v165
	v_lshl_or_b32 v2, v0, 10, v55
	v_or_b32_e32 v1, 4, v0
	v_bitop3_b32 v0, v0, v165, 4 bitop3:0x36
	s_add_i32 s21, s13, 0
	s_and_b32 s9, s9, 0x3fffffc0
	v_and_b32_e32 v53, 48, v8
	v_lshlrev_b32_e32 v56, 6, v179
	v_lshlrev_b32_e32 v0, 4, v0
	s_add_i32 m0, s21, 0x4000
	s_lshl_b32 s9, s9, 2
	v_or3_b32 v188, v54, v53, v56
	v_and_b32_e32 v57, 0xf0, v0
	global_load_lds_dwordx4 v2, s[40:41]
	s_mov_b32 m0, s21
	s_add_i32 s9, s9, 0
	v_lshl_or_b32 v3, v1, 10, v57
	global_load_lds_dwordx4 v188, s[48:49]
	s_add_i32 m0, s21, 0x4400
	s_add_i32 s9, s9, 0x22000
	s_or_b32 s39, s13, 0x400
	global_load_lds_dwordx4 v3, s[40:41]
	s_add_i32 m0, s21, 0x400
	s_add_u32 s30, s40, 0x10000
	v_lshl_add_u64 v[0:1], s[48:49], 0, v[188:189]
	s_addc_u32 s31, s41, 0
	v_lshl_add_u64 v[0:1], v[0:1], 0, s[34:35]
	s_add_u32 s50, s48, 0x10000
	global_load_lds_dwordx4 v[0:1], off
	s_addc_u32 s51, s49, 0
	s_add_i32 m0, s21, 0xc000
	v_or_b32_e32 v4, 0x80, v188
	global_load_lds_dwordx4 v2, s[30:31]
	s_add_i32 m0, s21, 0x8000
	v_and_b32_e32 v12, 0xf0, v8
	global_load_lds_dwordx4 v188, s[50:51]
	s_add_i32 m0, s21, 0xc400
	v_and_b32_e32 v58, 63, v165
	global_load_lds_dwordx4 v3, s[30:31]
	s_add_i32 m0, s21, 0x8400
	s_add_u32 s30, s40, 0x20000
	s_addc_u32 s31, s41, 0
	s_add_u32 s40, s48, 0x20000
	s_addc_u32 s41, s49, 0
	s_add_i32 s44, 0, 0x14000
	global_load_lds_dwordx4 v4, s[50:51]
	s_add_i32 m0, s44, s13
	s_add_i32 s48, 0, 0x10000
	global_load_lds_dwordx4 v2, s[30:31]
	s_add_i32 m0, s48, s13
	v_lshlrev_b32_e32 v14, 3, v58
	global_load_lds_dwordx4 v188, s[40:41]
	s_add_i32 m0, s44, s39
	v_or3_b32 v188, v54, v56, v53
	global_load_lds_dwordx4 v3, s[30:31]
	s_add_i32 m0, s48, s39
	s_cmp_lg_u32 0, -1
	global_load_lds_dwordx4 v4, s[40:41]
	s_cselect_b32 s13, 0, 0
	s_lshl_b32 s12, s12, 7
	v_bitop3_b32 v204, s12, v12, v166 bitop3:0x36
	v_add_u32_e32 v202, v204, v182
	v_add_u32_e32 v4, 0, v202
	s_waitcnt vmcnt(0)
	s_waitcnt vmcnt(0) lgkmcnt(0)
	s_barrier
; template <bool FIRST> __device__ __forceinline__ void partialSM(f32x16& p0, f32x16& p1, float& m_reg, f32x16& negm, float& alpha) {
;   float pmax = p0[0];
; #pragma unroll
;   for (int r = 1; r < 16; ++r) pmax = fmaxf(pmax, p0[r]);
; #pragma unroll
;   for (int r = 0; r < 16; ++r) pmax = fmaxf(pmax, p1[r]);
;   { auto rr = __builtin_amdgcn_permlane32_swap(__float_as_uint(pmax), __float_as_uint(pmax), false, false);
;     pmax = fmaxf(__uint_as_float(rr[0]), __uint_as_float(rr[1])); }
;   alpha = 1.f;
;   if (FIRST || __builtin_expect(__any(pmax > THR), 0)) { const float dl = FIRST ? pmax : fmaxf(pmax, 0.f); m_reg += dl; if (!FIRST) alpha = __builtin_amdgcn_exp2f(-dl);
; #pragma unroll
;     for (int r = 0; r < 16; ++r) { p0[r] -= dl; p1[r] -= dl; }
; #pragma unroll
;     for (int r = 0; r < 16; ++r) negm[r] = -m_reg; }
; #pragma unroll
;   for (int r = 0; r < 16; ++r) p0[r] = __builtin_amdgcn_exp2f(p0[r]);
; }
; __device__ __forceinline__ void finishSM(f32x16& p0, f32x16& p1, float alpha, float& l_reg, bf16x8& pa0, bf16x8& pa1, bf16x8& pa2, bf16x8& pa3) {
; #pragma unroll
;   for (int r = 0; r < 16; ++r) p1[r] = __builtin_amdgcn_exp2f(p1[r]);
;   float ps = 0;
; #pragma unroll
;   for (int r = 0; r < 16; ++r) ps += p0[r];
; #pragma unroll
;   for (int r = 0; r < 16; ++r) ps += p1[r];
;   { auto rr = __builtin_amdgcn_permlane32_swap(__float_as_uint(ps), __float_as_uint(ps), false, false);
;     ps = __uint_as_float(rr[0]) + __uint_as_float(rr[1]); }
;   l_reg = l_reg * alpha + ps;
;     ...
;   ATT_PKN(p0, 0, pa0); ATT_PKN(p0, 8, pa1); ATT_PKN(p1, 0, pa2); ATT_PKN(p1, 8, pa3);
;     ...
; }
; __device__ __forceinline__ void qkt(f32x16& p0, f32x16& p1, const bf16* Ks, const bf16x8* qr, int r32, int hi, int mp, const f32x16& negm) {
; #pragma unroll
;   for (int d0 = 0; d0 < 4; ++d0) { int cb = ((mp * 4 + d0) * 16 + hi * 8) * 2;
;     bf16x8 b0 = *reinterpret_cast<const bf16x8*>((const char*)Ks + KSWZ(r32, cb));
;     bf16x8 b1 = *reinterpret_cast<const bf16x8*>((const char*)Ks + KSWZ(32 + r32, cb));
;     if (d0 == 0) { p0 = __builtin_amdgcn_mfma_f32_32x32x16_bf16(b0, qr[0], negm, 0, 0, 0); p1 = __builtin_amdgcn_mfma_f32_32x32x16_bf16(b1, qr[0], negm, 0, 0, 0); }
;     else { p0 = __builtin_amdgcn_mfma_f32_32x32x16_bf16(b0, qr[d0], p0, 0, 0, 0); p1 = __builtin_amdgcn_mfma_f32_32x32x16_bf16(b1, qr[d0], p1, 0, 0, 0); } }
; }
	ds_read_b128 v[0:3], v4 offset:16384
	ds_read_b128 v[4:7], v4 offset:24576
	s_waitcnt lgkmcnt(1)
	v_mfma_f32_32x32x16_bf16 v[32:47], v[0:3], v[158:161], 0
	v_or_b32_e32 v13, s12, v166
	v_bitop3_b32 v203, v13, v12, 32 bitop3:0x36
	v_add_u32_e32 v201, v203, v182
	v_bitop3_b32 v200, v13, v12, 64 bitop3:0x36
	v_add_u32_e32 v199, v200, v182
	s_movk_i32 s12, 0x60
	v_bitop3_b32 v198, v13, v12, s12 bitop3:0x36
	s_waitcnt lgkmcnt(0)
	v_mfma_f32_32x32x16_bf16 v[16:31], v[4:7], v[158:161], 0
	v_add_u32_e32 v4, 0, v201
	ds_read_b128 v[0:3], v4 offset:16384
	ds_read_b128 v[4:7], v4 offset:24576
	v_add_u32_e32 v183, v198, v182
	s_mov_b32 s48, 0
	s_mov_b32 s49, s48
	s_mov_b32 s50, s48
	s_mov_b32 s51, s48
	s_waitcnt lgkmcnt(1)
	v_mfma_f32_32x32x16_bf16 v[32:47], v[0:3], v[154:157], v[32:47]
	v_and_b32_e32 v0, 0xc0, v8
	v_add_u32_e32 v8, 0, v199
	v_and_or_b32 v15, v14, 24, v0
	ds_read_b128 v[0:3], v8 offset:24576
	ds_read_b128 v[8:11], v8 offset:16384
	s_mov_b32 s52, s48
	s_mov_b32 s53, s48
	s_mov_b32 s54, s48
	s_waitcnt lgkmcnt(2)
	v_mfma_f32_32x32x16_bf16 v[16:31], v[4:7], v[154:157], v[16:31]
	v_lshlrev_b32_e32 v4, 1, v165
	v_and_b32_e32 v4, 32, v4
	v_and_b32_e32 v5, 0x100, v14
	v_or3_b32 v181, v15, v4, v5
	v_add_u32_e32 v4, 0, v183
	ds_read_b128 v[48:51], v4 offset:24576
	ds_read_b128 v[4:7], v4 offset:16384
	s_mov_b32 s55, s48
	s_waitcnt lgkmcnt(2)
	v_mfma_f32_32x32x16_bf16 v[32:47], v[8:11], v[150:153], v[32:47]
	s_mov_b32 s56, s48
	s_mov_b32 s57, s48
	s_mov_b32 s58, s48
	s_mov_b32 s59, s48
	s_mov_b32 s60, s48
	s_mov_b32 s61, s48
	s_mov_b32 s62, s48
	v_mfma_f32_32x32x16_bf16 v[16:31], v[0:3], v[150:153], v[16:31]
	s_mov_b32 s63, s48
	s_or_b32 s10, vcc_lo, s10
	v_cmp_gt_u32_e64 s[40:41], 32, v58
	s_mov_b32 s44, 1
	s_mov_b32 s39, 0x8000
	v_add_u32_e32 v205, s13, v181
	v_lshl_add_u32 v167, v178, 2, s9
	s_waitcnt lgkmcnt(0)
	v_mfma_f32_32x32x16_bf16 v[32:47], v[4:7], v[146:149], v[32:47]
	v_mov_b64_e32 v[0:1], s[48:49]
	v_mov_b64_e32 v[14:15], s[62:63]
	v_mov_b64_e32 v[2:3], s[50:51]
	v_mov_b64_e32 v[4:5], s[52:53]
	v_mov_b64_e32 v[6:7], s[54:55]
	v_mov_b64_e32 v[8:9], s[56:57]
	v_mov_b64_e32 v[10:11], s[58:59]
	v_mfma_f32_32x32x16_bf16 v[16:31], v[48:51], v[146:149], v[16:31]
	s_nop 3
	v_max_f32_e32 v48, v33, v33
	v_max_f32_e32 v49, v32, v32
	v_max_f32_e32 v48, v49, v48
	v_max3_f32 v48, v48, v34, v35
	v_max3_f32 v48, v48, v36, v37
	v_max3_f32 v48, v48, v38, v39
	v_max3_f32 v48, v48, v40, v41
	v_max3_f32 v48, v48, v42, v43
	v_max3_f32 v48, v48, v44, v45
	v_max3_f32 v48, v48, v46, v47
	v_max3_f32 v48, v48, v16, v17
	v_max3_f32 v48, v48, v18, v19
	v_max3_f32 v48, v48, v20, v21
	v_max3_f32 v48, v48, v22, v23
	v_max3_f32 v48, v48, v24, v25
	v_max3_f32 v48, v48, v26, v27
	v_max3_f32 v48, v48, v28, v29
	v_max3_f32 v48, v48, v30, v31
	v_mov_b32_e32 v49, v48
	s_nop 1
	v_permlane32_swap_b32_e32 v48, v49
	v_max_f32_e32 v49, v49, v49
	v_max_f32_e32 v48, v48, v48
	v_max_f32_e32 v48, v48, v49
	v_sub_f32_e32 v32, v32, v48
	v_sub_f32_e32 v33, v33, v48
	v_sub_f32_e32 v34, v34, v48
	v_sub_f32_e32 v35, v35, v48
	v_sub_f32_e32 v36, v36, v48
	v_sub_f32_e32 v37, v37, v48
	v_sub_f32_e32 v38, v38, v48
	v_sub_f32_e32 v39, v39, v48
	v_sub_f32_e32 v40, v40, v48
	v_sub_f32_e32 v41, v41, v48
	v_sub_f32_e32 v42, v42, v48
	v_sub_f32_e32 v43, v43, v48
	v_sub_f32_e32 v44, v44, v48
	v_sub_f32_e32 v45, v45, v48
	v_sub_f32_e32 v46, v46, v48
	v_sub_f32_e32 v47, v47, v48
	v_exp_f32_e32 v172, v32
	v_exp_f32_e32 v174, v33
	v_exp_f32_e32 v175, v34
	v_exp_f32_e32 v211, v35
	v_exp_f32_e32 v212, v36
	v_exp_f32_e32 v215, v37
	v_exp_f32_e32 v216, v38
	v_exp_f32_e32 v233, v39
	v_exp_f32_e32 v173, v40
	v_exp_f32_e32 v176, v41
	v_exp_f32_e32 v177, v42
	v_exp_f32_e32 v213, v43
	v_exp_f32_e32 v214, v44
	v_exp_f32_e32 v217, v45
	v_exp_f32_e32 v232, v46
	v_exp_f32_e32 v234, v47
	v_add_f32_e32 v206, 0, v48
	v_sub_f32_e32 v96, v16, v48
	v_lshl_or_b32 v16, v52, 10, s11
	v_mov_b64_e32 v[12:13], s[60:61]
	v_sub_f32_e32 v111, v31, v48
	v_sub_f32_e32 v110, v30, v48
	v_sub_f32_e32 v109, v29, v48
	v_sub_f32_e32 v108, v28, v48
	v_sub_f32_e32 v107, v27, v48
	v_sub_f32_e32 v106, v26, v48
	v_sub_f32_e32 v105, v25, v48
	v_sub_f32_e32 v104, v24, v48
	v_sub_f32_e32 v103, v23, v48
	v_sub_f32_e32 v102, v22, v48
	v_sub_f32_e32 v101, v21, v48
	v_sub_f32_e32 v100, v20, v48
	v_sub_f32_e32 v99, v19, v48
	v_sub_f32_e32 v98, v18, v48
	v_sub_f32_e32 v97, v17, v48
	v_xor_b32_e32 v80, 0x80000000, v206
	s_add_u32 s50, s42, s10
	v_or_b32_e32 v168, v16, v55
	v_or3_b32 v170, v16, v57, s18
	v_mov_b64_e32 v[62:63], v[14:15]
	v_mov_b64_e32 v[46:47], v[14:15]
	v_mov_b64_e32 v[30:31], v[14:15]
	s_addc_u32 s51, s43, vcc_hi
	v_mov_b32_e32 v169, v189
	v_mov_b32_e32 v171, v189
	v_mov_b32_e32 v180, 0
	v_mov_b32_e32 v207, 1.0
	s_mov_b32 s56, 0x18000
	v_mov_b64_e32 v[60:61], v[12:13]
	v_mov_b64_e32 v[58:59], v[10:11]
	v_mov_b64_e32 v[56:57], v[8:9]
	v_mov_b64_e32 v[54:55], v[6:7]
	v_mov_b64_e32 v[52:53], v[4:5]
	v_mov_b64_e32 v[50:51], v[2:3]
	v_mov_b64_e32 v[48:49], v[0:1]
	v_mov_b64_e32 v[44:45], v[12:13]
	v_mov_b64_e32 v[42:43], v[10:11]
	v_mov_b64_e32 v[40:41], v[8:9]
	v_mov_b64_e32 v[38:39], v[6:7]
	v_mov_b64_e32 v[36:37], v[4:5]
	v_mov_b64_e32 v[34:35], v[2:3]
	v_mov_b64_e32 v[32:33], v[0:1]
	v_mov_b64_e32 v[28:29], v[12:13]
	v_mov_b64_e32 v[26:27], v[10:11]
	v_mov_b64_e32 v[24:25], v[8:9]
	v_mov_b64_e32 v[22:23], v[6:7]
	v_mov_b64_e32 v[20:21], v[4:5]
	v_mov_b64_e32 v[18:19], v[2:3]
	v_mov_b64_e32 v[16:17], v[0:1]
	v_mov_b32_e32 v81, v80
	v_mov_b32_e32 v82, v80
	v_mov_b32_e32 v83, v80
	v_mov_b32_e32 v84, v80
	v_mov_b32_e32 v85, v80
	v_mov_b32_e32 v86, v80
	v_mov_b32_e32 v87, v80
	v_mov_b32_e32 v88, v80
	v_mov_b32_e32 v89, v80
	v_mov_b32_e32 v90, v80
	v_mov_b32_e32 v91, v80
	v_mov_b32_e32 v92, v80
	v_mov_b32_e32 v93, v80
	v_mov_b32_e32 v94, v80
	v_mov_b32_e32 v95, v80
	v_readfirstlane_b32 s98, v218
	s_nop 3
	s_lshr_b32 s98, s98, 8
	s_cmp_eq_u32 s98, 0
	s_cbranch_scc0 .Lprio_skip
	s_setprio 1
